# scan phase: touch the cache lines of step s+2 with throw-away dword loads issued behind the real loads of step s+1 (L2 prefetch)
# speedup vs baseline: 1.0004x; 1.0004x over previous
; #define LAS __attribute__((address_space(3)))
; __device__ __forceinline__ void scan_issue(const Params& p, int s, int dir, int b, int h, int slice, u32x4 (&kreg)[4], u32x4 (&vreg)[2]) {
;     ...
;     const bf16_t* kt = (const bf16_t*)(p.ws + WS_KT) + (size_t)(ck * 4 + h) * 128 * 128;
; #pragma unroll
;     for (int i = 0; i < 4; ++i) { const int idx = t + 512 * i; kreg[i] = *(const u32x4*)(kt + (idx >> 4) * 128 + (idx & 15) * 8); }
;     const bf16_t* vt = (const bf16_t*)(p.ws + WS_VT) + ((size_t)(ck * 4 + h) * 256 + slice * 64) * 128;
; #pragma unroll
;     for (int i = 0; i < 2; ++i) { const int idx = t + 512 * i; vreg[i] = *(const u32x4*)(vt + (idx >> 4) * 128 + (idx & 15) * 8); }
; __device__ __forceinline__ void scan_phase(const Params& p, LAS unsigned char* lds) {
;     ...
;             if (s + 1 < 34) scan_issue(p, s + 1, dir, b, h, slice, kreg, vreg);
;             __syncthreads();
;             const float decay = scs[s * 4];
;             if (s >= 2) {
;                 const int cc = ck - 32 * b;
;                 bf16_t* cp = CP + (size_t)(chain * 32 + cc) * (272 * 128);
;                 const int col = 16 * wid + 4 * fq;
; #pragma unroll
;                 for (int nb = 0; nb < 4; ++nb) { u32x2 o; o.x = cvt_pk_bf16(st[nb][0], st[nb][1]); o.y = cvt_pk_bf16(st[nb][2], st[nb][3]); *(u32x2*)(cp + (size_t)(slice * 64 + nb * 16 + fr) * 128 + col) = o; }
;                 if (slice == 0) { u32x2 o; o.x = cvt_pk_bf16(st[4][0], st[4][1]); o.y = cvt_pk_bf16(st[4][2], st[4][3]); *(u32x2*)(cp + (size_t)(256 + fr) * 128 + col) = o;
;                     if (t == 0) MP[chain * 32 + cc] = scs[s * 4 + 1]; }
;             }
;             f32x4 acc[5];
; #pragma unroll
;             for (int nb = 0; nb < 5; ++nb) acc[nb] = (f32x4){0.f, 0.f, 0.f, 0.f};
; #pragma unroll
;             for (int kk = 0; kk < 4; ++kk) { const bf16x8 a = *(const LAS bf16x8*)(kT + (16 * wid + fr) * 136 + kk * 32 + fq * 8);
; #pragma unroll
;                 for (int nb = 0; nb < 5; ++nb) { const bf16x8 bv = *(const LAS bf16x8*)(wvT + (nb * 16 + fr) * 136 + kk * 32 + fq * 8);
;                     acc[nb] = __builtin_amdgcn_mfma_f32_16x16x32_bf16(a, bv, acc[nb], 0, 0, 0); } }
; #pragma unroll
;             for (int nb = 0; nb < 5; ++nb) st[nb] = st[nb] * decay + acc[nb];
.LBB0_1411:
	s_or_b64 exec, exec, s[20:21]
	s_lshl_b32 s71, s71, 5
	s_cmp_eq_u32 s70, 0
	s_cselect_b64 s[28:29], -1, 0
	s_and_b64 s[20:21], s[18:19], exec
	s_cselect_b32 s20, 0, 31
	s_or_b32 s20, s20, s66
	s_lshl_b32 s20, s20, 2
	s_or_b32 s20, s20, s65
	s_ashr_i32 s21, s20, 31
	s_lshl_b64 s[30:31], s[20:21], 15
	s_lshl_b64 s[20:21], s[20:21], 16
	v_lshl_add_u64 v[0:1], v[54:55], 0, s[30:31]
	v_mov_b32_e32 v59, v51
	s_add_u32 s20, s26, s20
	v_lshl_add_u64 v[2:3], v[0:1], 0, v[58:59]
	v_mov_b32_e32 v61, v51
	s_addc_u32 s21, s27, s21
	v_lshl_add_u64 v[4:5], v[0:1], 0, v[60:61]
	global_load_dwordx4 v[12:15], v[2:3], off
	global_load_dwordx4 v[8:11], v[4:5], off
	v_add_co_u32_e32 v2, vcc, s41, v2
	v_mov_b32_e32 v63, v51
	s_add_u32 s20, s20, s24
	v_addc_co_u32_e32 v3, vcc, 0, v3, vcc
	v_lshl_add_u64 v[0:1], v[0:1], 0, v[62:63]
	s_addc_u32 s21, s21, 0
	v_mov_b32_e32 v65, v51
	global_load_dwordx4 v[20:23], v[2:3], off
	global_load_dwordx4 v[16:19], v[0:1], off
	v_lshl_add_u64 v[0:1], s[20:21], 0, v[64:65]
	v_lshl_add_u64 v[2:3], v[0:1], 0, v[58:59]
	v_lshl_add_u64 v[0:1], v[0:1], 0, v[60:61]
	global_load_dwordx4 v[4:7], v[2:3], off
	s_nop 0
	global_load_dwordx4 v[0:3], v[0:1], off
	global_load_dword v160, v[54:55], off
	global_load_dword v161, v[54:55], off
	global_load_dword v162, v[54:55], off
	global_load_dword v163, v[54:55], off
	global_load_dword v164, v[54:55], off
	global_load_dword v165, v[54:55], off
	s_waitcnt lgkmcnt(0)
	s_barrier
	ds_read_b128 v[44:47], v91 offset:56576
	ds_read_b128 v[110:113], v103
	ds_read_b128 v[114:117], v103 offset:4352
	ds_read_b128 v[118:121], v103 offset:8704
	ds_read_b128 v[122:125], v103 offset:13056
	ds_read_b128 v[126:129], v103 offset:17408
	ds_read_b128 v[130:133], v91 offset:56640
	s_waitcnt lgkmcnt(5)
	v_mfma_f32_16x16x32_bf16 v[110:113], v[44:47], v[110:113], 0
	v_mov_b32_e32 v59, s44
	v_mul_f32_e32 v66, 0, v66
	v_pk_add_f32 v[150:151], v[66:67], v[26:27] op_sel_hi:[0,1]
	s_waitcnt lgkmcnt(4)
	v_mfma_f32_16x16x32_bf16 v[114:117], v[44:47], v[114:117], 0
	v_add_f32_e64 v34, v66, v34
	v_add_f32_e64 v35, v66, v35
	v_pk_add_f32 v[38:39], v[66:67], v[38:39] op_sel_hi:[0,1]
	v_pk_add_f32 v[36:37], v[66:67], v[36:37] op_sel_hi:[0,1]
	s_waitcnt lgkmcnt(3)
	v_mfma_f32_16x16x32_bf16 v[118:121], v[44:47], v[118:121], 0
	v_add_f32_e64 v42, v66, v42
	v_add_f32_e64 v43, v66, v43
	v_pk_add_f32 v[40:41], v[66:67], v[40:41] op_sel_hi:[0,1]
	s_mov_b32 s70, 0
	s_waitcnt lgkmcnt(2)
	v_mfma_f32_16x16x32_bf16 v[122:125], v[44:47], v[122:125], 0
	v_mov_b32_e32 v65, v102
	s_waitcnt lgkmcnt(1)
	v_mfma_f32_16x16x32_bf16 v[44:47], v[44:47], v[126:129], 0
	ds_read_b128 v[126:129], v103 offset:64
	s_waitcnt lgkmcnt(0)
	v_mfma_f32_16x16x32_bf16 v[110:113], v[130:133], v[126:129], v[110:113]
	ds_read_b128 v[126:129], v103 offset:4416
	s_waitcnt lgkmcnt(0)
	v_mfma_f32_16x16x32_bf16 v[114:117], v[130:133], v[126:129], v[114:117]
	ds_read_b128 v[126:129], v103 offset:8768
	s_waitcnt lgkmcnt(0)
	v_mfma_f32_16x16x32_bf16 v[118:121], v[130:133], v[126:129], v[118:121]
	ds_read_b128 v[126:129], v103 offset:13120
	ds_read_b128 v[134:137], v103 offset:17472
	s_waitcnt lgkmcnt(1)
	v_mfma_f32_16x16x32_bf16 v[122:125], v[130:133], v[126:129], v[122:125]
	ds_read_b128 v[126:129], v91 offset:56704
	s_waitcnt lgkmcnt(1)
	v_mfma_f32_16x16x32_bf16 v[44:47], v[130:133], v[134:137], v[44:47]
	ds_read_b128 v[130:133], v103 offset:128
	s_waitcnt lgkmcnt(0)
	v_mfma_f32_16x16x32_bf16 v[110:113], v[126:129], v[130:133], v[110:113]
	ds_read_b128 v[130:133], v103 offset:4480
	s_waitcnt lgkmcnt(0)
	v_mfma_f32_16x16x32_bf16 v[114:117], v[126:129], v[130:133], v[114:117]
	ds_read_b128 v[130:133], v103 offset:8832
	ds_read_b128 v[134:137], v103 offset:13184
	s_waitcnt lgkmcnt(1)
	v_mfma_f32_16x16x32_bf16 v[118:121], v[126:129], v[130:133], v[118:121]
	ds_read_b128 v[130:133], v91 offset:56768
	ds_read_b128 v[142:145], v103 offset:17536
	s_waitcnt lgkmcnt(2)
	v_mfma_f32_16x16x32_bf16 v[122:125], v[126:129], v[134:137], v[122:125]
	ds_read_b32 v138, v59
	ds_read_b128 v[134:137], v103 offset:13248
	ds_read_b128 v[146:149], v103 offset:192
	s_waitcnt lgkmcnt(3)
	v_mfma_f32_16x16x32_bf16 v[44:47], v[126:129], v[142:145], v[44:47]
	ds_read_b128 v[126:129], v103 offset:8896
	ds_read_b128 v[142:145], v103 offset:4544
	s_waitcnt lgkmcnt(0)
	v_mfma_f32_16x16x32_bf16 v[114:117], v[130:133], v[142:145], v[114:117]
	v_add_f32_e64 v142, v66, v24
	v_add_f32_e64 v143, v66, v25
	ds_read_b128 v[24:27], v103 offset:17600
	v_pk_add_f32 v[144:145], v[66:67], v[32:33] op_sel_hi:[0,1]
	v_mfma_f32_16x16x32_bf16 v[110:113], v[130:133], v[146:149], v[110:113]
	v_add_f32_e64 v146, v66, v30
	v_add_f32_e64 v147, v66, v31
	v_pk_add_f32 v[148:149], v[66:67], v[28:29] op_sel_hi:[0,1]
	v_mfma_f32_16x16x32_bf16 v[118:121], v[130:133], v[126:129], v[118:121]
	v_mfma_f32_16x16x32_bf16 v[30:33], v[130:133], v[134:137], v[122:125]
	s_waitcnt lgkmcnt(0)
	v_mfma_f32_16x16x32_bf16 v[26:29], v[130:133], v[24:27], v[44:47]
	s_nop 2
	v_or_b32_e32 v44, s67, v52
	s_nop 1
	v_pk_fma_f32 v[30:31], v[36:37], v[138:139], v[30:31] op_sel_hi:[1,0,1]
	s_nop 0
	v_pk_fma_f32 v[24:25], v[42:43], v[138:139], v[28:29] op_sel_hi:[1,0,1]
	v_pk_fma_f32 v[26:27], v[40:41], v[138:139], v[26:27] op_sel_hi:[1,0,1]
	v_pk_fma_f32 v[28:29], v[38:39], v[138:139], v[32:33] op_sel_hi:[1,0,1]
	v_pk_fma_f32 v[32:33], v[34:35], v[138:139], v[120:121] op_sel_hi:[1,0,1]
	v_pk_fma_f32 v[34:35], v[144:145], v[138:139], v[118:119] op_sel_hi:[1,0,1]
	v_pk_fma_f32 v[36:37], v[150:151], v[138:139], v[116:117] op_sel_hi:[1,0,1]
	v_pk_fma_f32 v[38:39], v[142:143], v[138:139], v[114:115] op_sel_hi:[1,0,1]
	v_pk_fma_f32 v[40:41], v[146:147], v[138:139], v[112:113] op_sel_hi:[1,0,1]
	v_pk_fma_f32 v[42:43], v[148:149], v[138:139], v[110:111] op_sel_hi:[1,0,1]
	v_lshl_add_u64 v[46:47], v[56:57], 0, s[24:25]
	s_mov_b32 s24, 30
	v_lshlrev_b32_e32 v44, 1, v44
	s_mov_b32 s67, s63
	s_branch .LBB0_1414

; #define LAS __attribute__((address_space(3)))
; __device__ __forceinline__ unsigned cvt_pk_bf16(float lo, float hi) { unsigned r; asm volatile("v_cvt_pk_bf16_f32 %0, %1, %2" : "=v"(r) : "v"(lo), "v"(hi)); return r; }
; __device__ __forceinline__ float bflo(unsigned u) { return __uint_as_float(u << 16); }
; __device__ __forceinline__ float bfhi(unsigned u) { return __uint_as_float(u & 0xffff0000u); }
; __device__ __forceinline__ void scan_phase(const Params& p, LAS unsigned char* lds) {
;     ...
;             LAS bf16_t* kT = (LAS bf16_t*)(lds + (s & 1) * 56576);
;             LAS bf16_t* wvT = (LAS bf16_t*)(lds + (s & 1) * 56576 + 34816);
;             LAS float* wb = wls + s * 128;
; #pragma unroll
;             for (int i = 0; i < 4; ++i) { const int idx = t + 512 * i; *(LAS u32x4*)(kT + (idx >> 4) * 136 + (idx & 15) * 8) = kreg[i]; }
; #pragma unroll
;             for (int i = 0; i < 2; ++i) { const int idx = t + 512 * i, r = idx >> 4, c8 = (idx & 15) * 8;
;                 const f32x4 w0 = *(const LAS f32x4*)(wb + c8), w1 = *(const LAS f32x4*)(wb + c8 + 4);
;                 u32x4 o; o.x = cvt_pk_bf16(bflo(vreg[i].x) * w0[0], bfhi(vreg[i].x) * w0[1]); o.y = cvt_pk_bf16(bflo(vreg[i].y) * w0[2], bfhi(vreg[i].y) * w0[3]);
;                 o.z = cvt_pk_bf16(bflo(vreg[i].z) * w1[0], bfhi(vreg[i].z) * w1[1]); o.w = cvt_pk_bf16(bflo(vreg[i].w) * w1[2], bfhi(vreg[i].w) * w1[3]);
;                 *(LAS u32x4*)(wvT + r * 136 + c8) = o; }
;             if (t < 256) { const int r = 64 + (t >> 4), c8 = (t & 15) * 8; u32x4 o = (u32x4){0u, 0u, 0u, 0u};
;                 if (r == 64) { const f32x4 w0 = *(const LAS f32x4*)(wb + c8), w1 = *(const LAS f32x4*)(wb + c8 + 4);
;                     o.x = cvt_pk_bf16(w0[0], w0[1]); o.y = cvt_pk_bf16(w0[2], w0[3]); o.z = cvt_pk_bf16(w1[0], w1[1]); o.w = cvt_pk_bf16(w1[2], w1[3]); }
;                 *(LAS u32x4*)(wvT + r * 136 + c8) = o; }
.LBB0_1414:
	s_bitcmp1_b32 s70, 0
	s_cselect_b32 s20, 0xdd00, 0
	s_add_i32 s80, s20, 0
	v_lshl_add_u32 v45, v48, 1, s80
	v_add_u32_e32 v59, v45, v69
	v_add_u32_e32 v61, v45, v86
	s_waitcnt vmcnt(11)
	ds_write_b128 v59, v[12:15]
	s_waitcnt vmcnt(10)
	ds_write_b128 v61, v[8:11]
	s_waitcnt vmcnt(9)
	ds_write_b128 v59, v[20:23] offset:17408
	v_add_u32_e32 v8, v45, v87
	s_waitcnt vmcnt(8)
	ds_write_b128 v8, v[16:19]
	ds_read_b128 v[8:11], v65
	ds_read_b128 v[12:15], v65 offset:16
	s_waitcnt vmcnt(7)
	v_lshlrev_b32_e32 v16, 16, v4
	v_and_b32_e32 v4, 0xffff0000, v4
	s_waitcnt lgkmcnt(1)
	v_mul_f32_e32 v8, v8, v16
	v_mul_f32_e32 v4, v9, v4
	v_cvt_pk_bf16_f32 v4, v8, v4
	v_lshlrev_b32_e32 v8, 16, v5
	v_and_b32_e32 v5, 0xffff0000, v5
	v_mul_f32_e32 v8, v10, v8
	v_mul_f32_e32 v5, v11, v5
	v_cvt_pk_bf16_f32 v5, v8, v5
	v_lshlrev_b32_e32 v8, 16, v6
	v_and_b32_e32 v6, 0xffff0000, v6
	s_waitcnt lgkmcnt(0)
	v_mul_f32_e32 v8, v12, v8
	v_mul_f32_e32 v6, v13, v6
	v_cvt_pk_bf16_f32 v6, v8, v6
	v_lshlrev_b32_e32 v8, 16, v7
	v_and_b32_e32 v7, 0xffff0000, v7
	v_mul_f32_e32 v7, v15, v7
	v_mul_f32_e32 v8, v14, v8
	v_cvt_pk_bf16_f32 v7, v8, v7
	ds_write_b128 v59, v[4:7] offset:34816
	ds_read_b128 v[4:7], v65
	ds_read_b128 v[8:11], v65 offset:16
	s_waitcnt vmcnt(6)
	v_lshlrev_b32_e32 v12, 16, v0
	v_and_b32_e32 v0, 0xffff0000, v0
	s_waitcnt lgkmcnt(1)
	v_mul_f32_e32 v4, v4, v12
	v_mul_f32_e32 v0, v5, v0
	v_cvt_pk_bf16_f32 v0, v4, v0
	v_lshlrev_b32_e32 v4, 16, v1
	v_and_b32_e32 v1, 0xffff0000, v1
	v_mul_f32_e32 v4, v6, v4
	v_mul_f32_e32 v1, v7, v1
	v_cvt_pk_bf16_f32 v1, v4, v1
	v_lshlrev_b32_e32 v4, 16, v2
	v_and_b32_e32 v2, 0xffff0000, v2
	s_waitcnt lgkmcnt(0)
	v_mul_f32_e32 v4, v8, v4
	v_mul_f32_e32 v2, v9, v2
	v_cvt_pk_bf16_f32 v2, v4, v2
	v_lshlrev_b32_e32 v4, 16, v3
	v_and_b32_e32 v3, 0xffff0000, v3
	v_mul_f32_e32 v3, v11, v3
	v_mul_f32_e32 v4, v10, v4
	v_cvt_pk_bf16_f32 v3, v4, v3
	ds_write_b128 v61, v[0:3] offset:34816
	s_and_saveexec_b64 s[20:21], s[14:15]
	s_cbranch_execz .LBB0_1418
	v_mov_b32_e32 v0, 0
	v_mov_b32_e32 v1, 0
	v_mov_b32_e32 v2, 0
	v_mov_b32_e32 v3, 0
	s_and_saveexec_b64 s[30:31], s[16:17]
	s_cbranch_execz .LBB0_1417
	ds_read_b128 v[0:3], v65
	ds_read_b128 v[4:7], v65 offset:16
	s_waitcnt lgkmcnt(1)
	v_cvt_pk_bf16_f32 v0, v0, v1
	v_cvt_pk_bf16_f32 v1, v2, v3
	s_waitcnt lgkmcnt(0)
	v_cvt_pk_bf16_f32 v2, v4, v5
	v_cvt_pk_bf16_f32 v3, v6, v7

; __device__ __forceinline__ void scan_issue(const Params& p, int s, int dir, int b, int h, int slice, u32x4 (&kreg)[4], u32x4 (&vreg)[2]) {
;     const int t = threadIdx.x;
;     const int ck = scan_chunk(s, dir, b);
; __device__ __forceinline__ void scan_phase(const Params& p, LAS unsigned char* lds) {
;     ...
;             for (int i = 0; i < 4; ++i) { const int idx = t + 512 * i; *(LAS u32x4*)(kT + (idx >> 4) * 136 + (idx & 15) * 8) = kreg[i]; }
; #pragma unroll
;             for (int i = 0; i < 2; ++i) { const int idx = t + 512 * i, r = idx >> 4, c8 = (idx & 15) * 8;
;                 const f32x4 w0 = *(const LAS f32x4*)(wb + c8), w1 = *(const LAS f32x4*)(wb + c8 + 4);
;                 u32x4 o; o.x = cvt_pk_bf16(bflo(vreg[i].x) * w0[0], bfhi(vreg[i].x) * w0[1]); o.y = cvt_pk_bf16(bflo(vreg[i].y) * w0[2], bfhi(vreg[i].y) * w0[3]);
;                 o.z = cvt_pk_bf16(bflo(vreg[i].z) * w1[0], bfhi(vreg[i].z) * w1[1]); o.w = cvt_pk_bf16(bflo(vreg[i].w) * w1[2], bfhi(vreg[i].w) * w1[3]);
;                 *(LAS u32x4*)(wvT + r * 136 + c8) = o; }
;             if (t < 256) { const int r = 64 + (t >> 4), c8 = (t & 15) * 8; u32x4 o = (u32x4){0u, 0u, 0u, 0u};
;                 if (r == 64) { const f32x4 w0 = *(const LAS f32x4*)(wb + c8), w1 = *(const LAS f32x4*)(wb + c8 + 4);
;                     o.x = cvt_pk_bf16(w0[0], w0[1]); o.y = cvt_pk_bf16(w0[2], w0[3]); o.z = cvt_pk_bf16(w1[0], w1[1]); o.w = cvt_pk_bf16(w1[2], w1[3]); }
;                 *(LAS u32x4*)(wvT + r * 136 + c8) = o; }
;             const int ck = scan_chunk(s, dir, b);
;             if (s + 1 < 34) scan_issue(p, s + 1, dir, b, h, slice, kreg, vreg);
;             __syncthreads();
;             const float decay = scs[s * 4];
;             if (s >= 2) {
;                 const int cc = ck - 32 * b;
;                 bf16_t* cp = CP + (size_t)(chain * 32 + cc) * (272 * 128);
;                 const int col = 16 * wid + 4 * fq;
; #pragma unroll
;                 for (int nb = 0; nb < 4; ++nb) { u32x2 o; o.x = cvt_pk_bf16(st[nb][0], st[nb][1]); o.y = cvt_pk_bf16(st[nb][2], st[nb][3]); *(u32x2*)(cp + (size_t)(slice * 64 + nb * 16 + fr) * 128 + col) = o; }
;                 if (slice == 0) { u32x2 o; o.x = cvt_pk_bf16(st[4][0], st[4][1]); o.y = cvt_pk_bf16(st[4][2], st[4][3]); *(u32x2*)(cp + (size_t)(256 + fr) * 128 + col) = o;
;                     if (t == 0) MP[chain * 32 + cc] = scs[s * 4 + 1]; }
.LBB0_1418:
	s_or_b64 exec, exec, s[20:21]
	s_add_i32 s30, s24, 1
	s_and_b64 s[20:21], s[18:19], exec
	s_cselect_b32 s34, s70, s30
	s_add_i32 s70, s70, 1
	s_and_b64 s[20:21], s[18:19], exec
	s_cselect_b32 s20, s70, s24
	s_add_i32 s20, s20, s66
	s_lshl_b32 s20, s20, 2
	s_or_b32 s20, s20, s65
	s_ashr_i32 s21, s20, 31
	s_lshl_b64 s[30:31], s[20:21], 15
	v_lshl_add_u64 v[0:1], v[54:55], 0, s[30:31]
	v_mov_b32_e32 v59, v51
	v_lshl_add_u64 v[2:3], v[0:1], 0, v[58:59]
	v_mov_b32_e32 v61, v51
	v_lshl_add_u64 v[4:5], v[0:1], 0, v[60:61]
	global_load_dwordx4 v[12:15], v[2:3], off
	global_load_dwordx4 v[8:11], v[4:5], off
	v_add_co_u32_e32 v2, vcc, s41, v2
	v_mov_b32_e32 v63, v51
	s_nop 0
	v_addc_co_u32_e32 v3, vcc, 0, v3, vcc
	v_lshl_add_u64 v[0:1], v[0:1], 0, v[62:63]
	s_lshl_b64 s[20:21], s[20:21], 16
	global_load_dwordx4 v[20:23], v[2:3], off
	global_load_dwordx4 v[16:19], v[0:1], off
	v_lshl_add_u64 v[0:1], v[46:47], 0, s[20:21]
	v_lshl_add_u64 v[2:3], v[0:1], 0, v[58:59]
	v_lshl_add_u64 v[0:1], v[0:1], 0, v[60:61]
	global_load_dwordx4 v[4:7], v[2:3], off
	s_nop 0
	global_load_dwordx4 v[0:3], v[0:1], off
	s_and_b64 s[98:99], s[18:19], exec
	s_cselect_b32 s100, 1, -1
	s_lshl_b32 s100, s100, 17
	s_ashr_i32 s101, s100, 31
	s_add_u32 s98, s30, s100
	s_addc_u32 s99, s31, s101
	v_lshl_add_u64 v[152:153], v[54:55], 0, s[98:99]
	v_lshl_add_u64 v[154:155], v[152:153], 0, v[58:59]
	v_lshl_add_u64 v[156:157], v[152:153], 0, v[60:61]
	v_lshl_add_u64 v[158:159], v[152:153], 0, v[62:63]
	global_load_dword v160, v[154:155], off
	global_load_dword v161, v[156:157], off
	global_load_dword v162, v[158:159], off
	v_add_co_u32_e32 v154, vcc, s41, v154
	s_nop 1
	v_addc_co_u32_e32 v155, vcc, 0, v155, vcc
	global_load_dword v163, v[154:155], off
	s_lshl_b32 s100, s100, 1
	s_ashr_i32 s101, s100, 31
	s_add_u32 s98, s20, s100
	s_addc_u32 s99, s21, s101
	v_lshl_add_u64 v[152:153], v[46:47], 0, s[98:99]
	v_lshl_add_u64 v[154:155], v[152:153], 0, v[58:59]
	v_lshl_add_u64 v[156:157], v[152:153], 0, v[60:61]
	global_load_dword v164, v[154:155], off
	global_load_dword v165, v[156:157], off
	s_add_i32 s30, s34, s71
	s_add_i32 s20, s67, -4
	s_mul_i32 s21, s30, 0x11000
	v_mov_b32_e32 v45, s20
	s_mul_hi_i32 s20, s30, 0x11000
	s_add_u32 s34, s3, s21
	s_addc_u32 s35, s33, s20
	s_waitcnt lgkmcnt(0)
	s_barrier
	ds_read_b32 v66, v45
	v_lshl_add_u64 v[110:111], s[34:35], 0, v[50:51]
	v_mov_b32_e32 v45, v51
	v_lshl_add_u64 v[110:111], v[110:111], 0, v[44:45]
	v_add_co_u32_e32 v114, vcc, s40, v110
	v_cvt_pk_bf16_f32 v112, v42, v43
	v_cvt_pk_bf16_f32 v113, v40, v41
	global_store_dwordx2 v[110:111], v[112:113], off
	s_nop 0
	v_addc_co_u32_e32 v115, vcc, 0, v111, vcc
	v_cvt_pk_bf16_f32 v112, v38, v39
	v_cvt_pk_bf16_f32 v113, v36, v37
	global_store_dwordx2 v[114:115], v[112:113], off
	v_add_co_u32_e32 v114, vcc, 0x2000, v110
	v_cndmask_b32_e64 v45, 0, 1, s[28:29]
	s_nop 0
	v_addc_co_u32_e32 v115, vcc, 0, v111, vcc
	v_add_co_u32_e32 v110, vcc, 0x3000, v110
	v_cvt_pk_bf16_f32 v112, v34, v35
	v_cvt_pk_bf16_f32 v113, v32, v33
	v_cmp_ne_u32_e64 s[20:21], 1, v45
	s_nop 0
	v_addc_co_u32_e32 v111, vcc, 0, v111, vcc
	s_andn2_b64 vcc, exec, s[28:29]
	global_store_dwordx2 v[114:115], v[112:113], off
	v_cvt_pk_bf16_f32 v112, v30, v31
	v_cvt_pk_bf16_f32 v113, v28, v29
	global_store_dwordx2 v[110:111], v[112:113], off
	s_cbranch_vccnz .LBB0_1413
	v_lshlrev_b32_e32 v112, 1, v52
	v_mov_b32_e32 v113, v51
	v_lshl_add_u64 v[112:113], s[34:35], 0, v[112:113]
	v_lshl_add_u64 v[112:113], v[112:113], 0, v[50:51]
	v_add_co_u32_e32 v112, vcc, 0x10000, v112
	v_cvt_pk_bf16_f32 v110, v26, v27
	v_cvt_pk_bf16_f32 v111, v24, v25
	s_nop 1
	v_addc_co_u32_e32 v113, vcc, 0, v113, vcc
	global_store_dwordx2 v[112:113], v[110:111], off
	s_and_saveexec_b64 s[34:35], s[68:69]
	s_cbranch_execz .LBB0_1412
	v_mov_b32_e32 v45, s67
	ds_read_b32 v45, v45
	s_ashr_i32 s31, s30, 31
	s_lshl_b64 s[30:31], s[30:31], 2
	s_add_u32 s30, s36, s30
	s_addc_u32 s31, s37, s31
	s_waitcnt lgkmcnt(0)
	global_store_dword v51, v45, s[30:31]
	s_branch .LBB0_1412
.LBB0_1421:
	s_waitcnt vmcnt(15)
	ds_write_b128 v105, v[12:15] offset:56576
	s_waitcnt vmcnt(14)
	ds_write_b128 v106, v[8:11] offset:56576
	s_waitcnt vmcnt(13)
	ds_write_b128 v104, v[20:23] offset:56576
	s_waitcnt vmcnt(12)
	ds_write_b128 v107, v[16:19] offset:56576
	ds_read_b128 v[8:11], v88 offset:16896
	ds_read_b128 v[12:15], v88 offset:16912
	s_waitcnt vmcnt(11)
	v_lshlrev_b32_e32 v16, 16, v4
	v_and_b32_e32 v4, 0xffff0000, v4
	s_waitcnt lgkmcnt(1)
	v_mul_f32_e32 v8, v8, v16
	v_mul_f32_e32 v4, v9, v4
	v_cvt_pk_bf16_f32 v4, v8, v4
	v_lshlrev_b32_e32 v8, 16, v5
	v_and_b32_e32 v5, 0xffff0000, v5
	v_mul_f32_e32 v8, v10, v8
	v_mul_f32_e32 v5, v11, v5
	v_cvt_pk_bf16_f32 v5, v8, v5
	v_lshlrev_b32_e32 v8, 16, v6
	v_and_b32_e32 v6, 0xffff0000, v6
	s_waitcnt lgkmcnt(0)
	v_mul_f32_e32 v8, v12, v8
	v_mul_f32_e32 v6, v13, v6
	v_cvt_pk_bf16_f32 v6, v8, v6
	v_lshlrev_b32_e32 v8, 16, v7
	v_and_b32_e32 v7, 0xffff0000, v7
	v_mul_f32_e32 v7, v15, v7
	v_mul_f32_e32 v8, v14, v8
	v_cvt_pk_bf16_f32 v7, v8, v7
	ds_write_b128 v108, v[4:7]
	ds_read_b128 v[4:7], v88 offset:16896
	ds_read_b128 v[8:11], v88 offset:16912
	s_waitcnt vmcnt(10)
	v_lshlrev_b32_e32 v12, 16, v0
	v_and_b32_e32 v0, 0xffff0000, v0
	s_waitcnt lgkmcnt(1)
	v_mul_f32_e32 v4, v4, v12
	v_mul_f32_e32 v0, v5, v0
	v_cvt_pk_bf16_f32 v0, v4, v0
	v_lshlrev_b32_e32 v4, 16, v1
	v_and_b32_e32 v1, 0xffff0000, v1
	v_mul_f32_e32 v4, v6, v4
	v_mul_f32_e32 v1, v7, v1
	v_cvt_pk_bf16_f32 v1, v4, v1
	v_lshlrev_b32_e32 v4, 16, v2
	v_and_b32_e32 v2, 0xffff0000, v2
	s_waitcnt lgkmcnt(0)
	v_mul_f32_e32 v4, v8, v4
	v_mul_f32_e32 v2, v9, v2
	v_cvt_pk_bf16_f32 v2, v4, v2
	v_lshlrev_b32_e32 v4, 16, v3
	v_and_b32_e32 v3, 0xffff0000, v3
	v_mul_f32_e32 v3, v11, v3
	v_mul_f32_e32 v4, v10, v4
	v_cvt_pk_bf16_f32 v3, v4, v3
	ds_write_b128 v109, v[0:3]
	s_and_saveexec_b64 s[28:29], s[14:15]
	s_cbranch_execz .LBB0_1425
	v_mov_b32_e32 v0, 0
	v_mov_b32_e32 v1, 0
	v_mov_b32_e32 v2, 0
	v_mov_b32_e32 v3, 0
	s_and_saveexec_b64 s[30:31], s[16:17]
	s_cbranch_execz .LBB0_1424
	ds_read_b128 v[0:3], v88 offset:16896
	ds_read_b128 v[4:7], v88 offset:16912
	s_waitcnt lgkmcnt(1)
	v_cvt_pk_bf16_f32 v0, v0, v1
	v_cvt_pk_bf16_f32 v1, v2, v3
	s_waitcnt lgkmcnt(0)
	v_cvt_pk_bf16_f32 v2, v4, v5
	v_cvt_pk_bf16_f32 v3, v6, v7
